# grid barrier: last leader skips the generation-word atomic and its completion wait
# speedup vs baseline: 1.0087x; 1.0041x over previous
; DI unsigned xb_ld(unsigned* p) { return __hip_atomic_load(p, __ATOMIC_RELAXED, __HIP_MEMORY_SCOPE_AGENT); }
; DI unsigned xb_add(unsigned* p, unsigned v) { return __hip_atomic_fetch_add(p, v, __ATOMIC_RELAXED, __HIP_MEMORY_SCOPE_AGENT); }
; #define XB_SPIN(cond, bar) do { unsigned _sp = 0; while (cond) { __builtin_amdgcn_s_sleep(1); \
;     if ((++_sp & 255u) == 0u) { if (xb_ld(&(bar)[XB_TMO])) break; if (_sp > XB_SPIN_CAP) { atomicAdd(&(bar)[XB_TMO], 1u); break; } } } } while (0)
; DI void xcd_barrier(unsigned* bar, const unsigned x, volatile LAS unsigned* st, const int tid) {
;     ...
;       const unsigned og = xb_add(&bar[XB_TOP], 1u);
;       const unsigned tg = og / nx;
;       if (og + 1u == (tg + 1u) * nx) xb_add(&bar[XB_TOPGEN], 1u);
;       else XB_SPIN(xb_ld(&bar[XB_TOPGEN]) == tg, bar);
.LBB0_1296:
	s_or_b64 exec, exec, s[4:5]
	s_waitcnt vmcnt(0)
	v_readfirstlane_b32 s2, v3
	v_sub_u32_e32 v4, 0, v2
	s_mov_b64 s[4:5], 0
	v_add_u32_e32 v3, s2, v0
	v_cvt_f32_u32_e32 v0, v2
	v_readlane_b32 s2, v252, 58
	v_readlane_b32 s3, v252, 59
	v_rcp_iflag_f32_e32 v0, v0
	s_nop 0
	v_mul_f32_e32 v0, 0x4f7ffffe, v0
	v_cvt_u32_f32_e32 v0, v0
	v_mul_lo_u32 v4, v4, v0
	v_mul_hi_u32 v4, v0, v4
	v_add_u32_e32 v0, v0, v4
	v_mul_hi_u32 v0, v3, v0
	v_mul_lo_u32 v4, v0, v2
	v_sub_u32_e32 v4, v3, v4
	v_cmp_ge_u32_e32 vcc, v4, v2
	v_add_u32_e32 v5, 1, v0
	v_add_u32_e32 v3, 1, v3
	v_cndmask_b32_e32 v0, v0, v5, vcc
	v_sub_u32_e32 v5, v4, v2
	v_cndmask_b32_e32 v4, v4, v5, vcc
	v_cmp_ge_u32_e32 vcc, v4, v2
	v_add_u32_e32 v4, 1, v0
	s_nop 0
	v_cndmask_b32_e32 v0, v0, v4, vcc
	v_mul_lo_u32 v4, v2, v0
	v_add_u32_e32 v2, v4, v2
	v_cmp_ne_u32_e32 vcc, v3, v2
	v_mov_b32_e32 v5, v2
	v_mov_b64_e32 v[2:3], s[2:3]
	s_and_saveexec_b64 s[2:3], vcc
	s_cbranch_execz .LBB0_1308
	v_readlane_b32 s4, v252, 56
	v_readlane_b32 s5, v252, 57
	s_mov_b64 s[6:7], 0
	s_nop 3
	global_load_dword v2, v1, s[4:5] sc1
	s_waitcnt vmcnt(0)
	v_cmp_lt_u32_e32 vcc, v2, v5
	s_and_saveexec_b64 s[4:5], vcc
	s_cbranch_execz .LBB0_1307
	s_mov_b32 s16, 1
	s_branch .LBB0_1300
